# stack + SGU LN-apply gamma/beta loads batched (16 loads, one wait instead of four serialized groups)
# baseline (speedup 1.0000x reference)
; #define LAS __attribute__((address_space(3)))
; __device__ __forceinline__ float bf_lo(unsigned w) { return __uint_as_float(w << 16); }
; __device__ __forceinline__ float bf_hi(unsigned w) { return __uint_as_float(w & 0xffff0000u); }
; __device__ __forceinline__ bf16_t f2bf(float f) { return (bf16_t)(cvt_pk_bf16(f, 0.f) & 0xffffu); }
; __device__ __forceinline__ void sgu_phase(const bf16_t* gu, const bf16_t* gv, const float* __restrict__ statsv, const float* __restrict__ lng, const float* __restrict__ lnb, const float* __restrict__ wsp, const float* __restrict__ bs, ...
;     ...
;         {
;             const int s = tid & 127; const float mean = st[2 * s], rstd = st[2 * s + 1];
; #pragma unroll
;             for (int i = 0; i < 4; ++i) {
;                 const int c8 = (tid >> 7) + 4 * i, col = g * 128 + c8 * 8;
;                 const u32x4 w = gvw[i];
;                 const f32x4 g0 = *(const f32x4*)(lng + col), g1 = *(const f32x4*)(lng + col + 4), b0 = *(const f32x4*)(lnb + col), b1 = *(const f32x4*)(lnb + col + 4);
;                 LAS bf16_t* vp = (LAS bf16_t*)(vT + (c8 * 8) * P) + s;
;                 vp[0 * (P / 2)] = f2bf((bf_lo(w.x) - mean) * rstd * g0[0] + b0[0]); vp[1 * (P / 2)] = f2bf((bf_hi(w.x) - mean) * rstd * g0[1] + b0[1]);
;                 vp[2 * (P / 2)] = f2bf((bf_lo(w.y) - mean) * rstd * g0[2] + b0[2]); vp[3 * (P / 2)] = f2bf((bf_hi(w.y) - mean) * rstd * g0[3] + b0[3]);
;                 vp[4 * (P / 2)] = f2bf((bf_lo(w.z) - mean) * rstd * g1[0] + b1[0]); vp[5 * (P / 2)] = f2bf((bf_hi(w.z) - mean) * rstd * g1[1] + b1[1]);
;                 vp[6 * (P / 2)] = f2bf((bf_lo(w.w) - mean) * rstd * g1[2] + b1[2]); vp[7 * (P / 2)] = f2bf((bf_hi(w.w) - mean) * rstd * g1[3] + b1[3]);
;             }
.LBB0_480:
	s_or_b64 exec, exec, s[76:77]
	s_and_b32 s79, s73, 0x380
	v_add_u32_e32 v58, s79, v94
	s_waitcnt lgkmcnt(1)
	v_ashrrev_i32_e32 v59, 31, v58
	v_lshlrev_b64 v[58:59], 2, v[58:59]
	v_lshl_add_u64 v[70:71], s[92:93], 0, v[58:59]
	v_lshl_add_u64 v[68:69], s[94:95], 0, v[58:59]
	s_waitcnt lgkmcnt(0)
	s_barrier
	ds_read_b64 v[66:67], v124
	global_load_dwordx4 v[62:65], v[70:71], off offset:16
	global_load_dwordx4 v[72:75], v[70:71], off
	global_load_dwordx4 v[58:61], v[68:69], off offset:16
	global_load_dwordx4 v[76:79], v[68:69], off
	global_load_dwordx4 v[142:145], v[70:71], off offset:144
	global_load_dwordx4 v[146:149], v[70:71], off offset:128
	global_load_dwordx4 v[150:153], v[68:69], off offset:144
	global_load_dwordx4 v[154:157], v[68:69], off offset:128
	global_load_dwordx4 v[158:161], v[70:71], off offset:272
	global_load_dwordx4 v[162:165], v[70:71], off offset:256
	global_load_dwordx4 v[166:169], v[68:69], off offset:272
	global_load_dwordx4 v[172:175], v[68:69], off offset:256
	global_load_dwordx4 v[176:179], v[70:71], off offset:400
	global_load_dwordx4 v[180:183], v[70:71], off offset:384
	global_load_dwordx4 v[184:187], v[68:69], off offset:400
	global_load_dwordx4 v[188:191], v[68:69], off offset:384
	v_lshlrev_b32_e32 v80, 16, v10
	v_readlane_b32 s76, v251, 8
	s_waitcnt lgkmcnt(0)
	v_sub_f32_e32 v80, v80, v66
	v_mul_f32_e32 v80, v67, v80
	s_add_i32 s78, s78, s76
	v_readlane_b32 s77, v251, 9
	s_cmpk_gt_i32 s78, 0x3ff
	s_cselect_b64 s[76:77], -1, 0
	s_and_b64 vcc, exec, s[76:77]
	s_waitcnt vmcnt(0)
	v_fma_f32 v72, v80, v72, v76
	v_cvt_pk_bf16_f32 v72, v72, v1
	ds_write_b16 v129, v72 offset:1024
	v_and_b32_e32 v72, 0xffff0000, v10
	v_sub_f32_e32 v72, v72, v66
	v_mul_f32_e32 v72, v67, v72
	v_fma_f32 v72, v72, v73, v77
	v_cvt_pk_bf16_f32 v72, v72, v1
	ds_write_b16 v129, v72 offset:1296
	v_lshlrev_b32_e32 v72, 16, v11
	v_sub_f32_e32 v72, v72, v66
	v_mul_f32_e32 v72, v67, v72
	v_fma_f32 v72, v72, v74, v78
	v_cvt_pk_bf16_f32 v72, v72, v1
	ds_write_b16 v129, v72 offset:1568
	v_and_b32_e32 v72, 0xffff0000, v11
	v_sub_f32_e32 v72, v72, v66
	v_mul_f32_e32 v72, v67, v72
	v_fmac_f32_e32 v79, v72, v75
	v_cvt_pk_bf16_f32 v72, v79, v1
	ds_write_b16 v129, v72 offset:1840
	v_lshlrev_b32_e32 v72, 16, v12
	v_sub_f32_e32 v72, v72, v66
	v_mul_f32_e32 v72, v67, v72
	v_fma_f32 v58, v72, v62, v58
	v_cvt_pk_bf16_f32 v58, v58, v1
	ds_write_b16 v129, v58 offset:2112
	v_and_b32_e32 v58, 0xffff0000, v12
	v_sub_f32_e32 v58, v58, v66
	v_mul_f32_e32 v58, v67, v58
	v_fma_f32 v58, v58, v63, v59
	v_cvt_pk_bf16_f32 v58, v58, v1
	ds_write_b16 v129, v58 offset:2384
	v_lshlrev_b32_e32 v58, 16, v13
	v_sub_f32_e32 v58, v58, v66
	v_mul_f32_e32 v58, v67, v58
	v_fma_f32 v58, v58, v64, v60
	v_cvt_pk_bf16_f32 v58, v58, v1
	ds_write_b16 v129, v58 offset:2656
	v_and_b32_e32 v58, 0xffff0000, v13
	v_sub_f32_e32 v58, v58, v66
	v_mul_f32_e32 v58, v67, v58
	v_fmac_f32_e32 v61, v58, v65
	v_cvt_pk_bf16_f32 v58, v61, v1
	ds_write_b16 v129, v58 offset:2928
	v_lshlrev_b32_e32 v80, 16, v14
	v_sub_f32_e32 v80, v80, v66
	v_mul_f32_e32 v80, v67, v80
	s_waitcnt vmcnt(0)
	v_fma_f32 v146, v80, v146, v154
	v_cvt_pk_bf16_f32 v146, v146, v1
	ds_write_b16 v129, v146 offset:9728
	v_and_b32_e32 v146, 0xffff0000, v14
	v_sub_f32_e32 v146, v146, v66
	v_mul_f32_e32 v146, v67, v146
	v_fma_f32 v146, v146, v147, v155
	v_cvt_pk_bf16_f32 v146, v146, v1
	ds_write_b16 v129, v146 offset:10000
	v_lshlrev_b32_e32 v146, 16, v15
	v_sub_f32_e32 v146, v146, v66
	v_mul_f32_e32 v146, v67, v146
	v_fma_f32 v146, v146, v148, v156
	v_cvt_pk_bf16_f32 v146, v146, v1
	ds_write_b16 v129, v146 offset:10272
	v_and_b32_e32 v146, 0xffff0000, v15
	v_sub_f32_e32 v146, v146, v66
	v_mul_f32_e32 v146, v67, v146
	v_fmac_f32_e32 v157, v146, v149
	v_cvt_pk_bf16_f32 v146, v157, v1
	ds_write_b16 v129, v146 offset:10544
	v_lshlrev_b32_e32 v146, 16, v16
	v_sub_f32_e32 v146, v146, v66
	v_mul_f32_e32 v146, v67, v146
	v_fma_f32 v150, v146, v142, v150
	v_cvt_pk_bf16_f32 v150, v150, v1
	ds_write_b16 v129, v150 offset:10816
	v_and_b32_e32 v150, 0xffff0000, v16
	v_sub_f32_e32 v150, v150, v66
	v_mul_f32_e32 v150, v67, v150
	v_fma_f32 v150, v150, v143, v151
	v_cvt_pk_bf16_f32 v150, v150, v1
	ds_write_b16 v129, v150 offset:11088
	v_lshlrev_b32_e32 v150, 16, v17
	v_sub_f32_e32 v150, v150, v66
	v_mul_f32_e32 v150, v67, v150
	v_fma_f32 v150, v150, v144, v152
	v_cvt_pk_bf16_f32 v150, v150, v1
	ds_write_b16 v129, v150 offset:11360
	v_and_b32_e32 v150, 0xffff0000, v17
	v_sub_f32_e32 v150, v150, v66
	v_mul_f32_e32 v150, v67, v150
	v_fmac_f32_e32 v153, v150, v145
	v_cvt_pk_bf16_f32 v150, v153, v1
	ds_write_b16 v129, v150 offset:11632
	v_lshlrev_b32_e32 v80, 16, v18
	v_sub_f32_e32 v80, v80, v66
	v_mul_f32_e32 v80, v67, v80
	s_waitcnt vmcnt(0)
	v_fma_f32 v162, v80, v162, v172
	v_cvt_pk_bf16_f32 v162, v162, v1
	ds_write_b16 v129, v162 offset:18432
	v_and_b32_e32 v162, 0xffff0000, v18
	v_sub_f32_e32 v162, v162, v66
	v_mul_f32_e32 v162, v67, v162
	v_fma_f32 v162, v162, v163, v173
	v_cvt_pk_bf16_f32 v162, v162, v1
	ds_write_b16 v129, v162 offset:18704
	v_lshlrev_b32_e32 v162, 16, v19
	v_sub_f32_e32 v162, v162, v66
	v_mul_f32_e32 v162, v67, v162
	v_fma_f32 v162, v162, v164, v174
	v_cvt_pk_bf16_f32 v162, v162, v1
	ds_write_b16 v129, v162 offset:18976
	v_and_b32_e32 v162, 0xffff0000, v19
	v_sub_f32_e32 v162, v162, v66
	v_mul_f32_e32 v162, v67, v162
	v_fmac_f32_e32 v175, v162, v165
	v_cvt_pk_bf16_f32 v162, v175, v1
	ds_write_b16 v129, v162 offset:19248
	v_lshlrev_b32_e32 v162, 16, v20
	v_sub_f32_e32 v162, v162, v66
	v_mul_f32_e32 v162, v67, v162
	v_fma_f32 v166, v162, v158, v166
	v_cvt_pk_bf16_f32 v166, v166, v1
	ds_write_b16 v129, v166 offset:19520
	v_and_b32_e32 v166, 0xffff0000, v20
	v_sub_f32_e32 v166, v166, v66
	v_mul_f32_e32 v166, v67, v166
	v_fma_f32 v166, v166, v159, v167
	v_cvt_pk_bf16_f32 v166, v166, v1
	ds_write_b16 v129, v166 offset:19792
	v_lshlrev_b32_e32 v166, 16, v21
	v_sub_f32_e32 v166, v166, v66
	v_mul_f32_e32 v166, v67, v166
	v_fma_f32 v166, v166, v160, v168
	v_cvt_pk_bf16_f32 v166, v166, v1
	ds_write_b16 v129, v166 offset:20064
	v_and_b32_e32 v166, 0xffff0000, v21
	v_sub_f32_e32 v166, v166, v66
	v_mul_f32_e32 v166, v67, v166
	v_fmac_f32_e32 v169, v166, v161
	v_cvt_pk_bf16_f32 v166, v169, v1
	ds_write_b16 v129, v166 offset:20336
	s_nop 0
	v_lshlrev_b32_e32 v68, 16, v22
	v_sub_f32_e32 v68, v68, v66
	v_mul_f32_e32 v68, v67, v68
	s_waitcnt vmcnt(0)
; #define LAS __attribute__((address_space(3)))
; __device__ __forceinline__ unsigned cvt_pk_bf16(float lo, float hi) { unsigned r; asm volatile("v_cvt_pk_bf16_f32 %0, %1, %2" : "=v"(r) : "v"(lo), "v"(hi)); return r; }
; __device__ __forceinline__ float bf_lo(unsigned w) { return __uint_as_float(w << 16); }
; __device__ __forceinline__ float bf_hi(unsigned w) { return __uint_as_float(w & 0xffff0000u); }
; __device__ __forceinline__ bf16_t f2bf(float f) { return (bf16_t)(cvt_pk_bf16(f, 0.f) & 0xffffu); }
; __device__ __forceinline__ void sgu_phase(const bf16_t* gu, const bf16_t* gv, const float* __restrict__ statsv, const float* __restrict__ lng, const float* __restrict__ lnb, const float* __restrict__ wsp, const float* __restrict__ bs, ...
;     ...
;                 vp[0 * (P / 2)] = f2bf((bf_lo(w.x) - mean) * rstd * g0[0] + b0[0]); vp[1 * (P / 2)] = f2bf((bf_hi(w.x) - mean) * rstd * g0[1] + b0[1]);
;                 vp[2 * (P / 2)] = f2bf((bf_lo(w.y) - mean) * rstd * g0[2] + b0[2]); vp[3 * (P / 2)] = f2bf((bf_hi(w.y) - mean) * rstd * g0[3] + b0[3]);
;                 vp[4 * (P / 2)] = f2bf((bf_lo(w.z) - mean) * rstd * g1[0] + b1[0]); vp[5 * (P / 2)] = f2bf((bf_hi(w.z) - mean) * rstd * g1[1] + b1[1]);
;                 vp[6 * (P / 2)] = f2bf((bf_lo(w.w) - mean) * rstd * g1[2] + b1[2]); vp[7 * (P / 2)] = f2bf((bf_hi(w.w) - mean) * rstd * g1[3] + b1[3]);
;             }
; #pragma unroll
;             for (int i = 0; i < 8; ++i) {
;                 const int t = (tid >> 5) + 16 * i, s4 = (tid & 31) * 4;
;                 u32x2 pk; pk.x = cvt_pk_bf16(s4 + 0 <= t ? wv[i][0] : 0.f, s4 + 1 <= t ? wv[i][1] : 0.f); pk.y = cvt_pk_bf16(s4 + 2 <= t ? wv[i][2] : 0.f, s4 + 3 <= t ? wv[i][3] : 0.f);
;                 *(LAS u32x2*)(Wl + t * P + s4 * 2) = pk;
;             }
;         }
;         __syncthreads();
;         if (u + (int)gridDim.x < 1024) SGU_LOAD(u + gridDim.x);
	v_fma_f32 v180, v68, v180, v188
	v_cvt_pk_bf16_f32 v180, v180, v1
	ds_write_b16 v129, v180 offset:27136
	v_and_b32_e32 v180, 0xffff0000, v22
	v_sub_f32_e32 v180, v180, v66
	v_mul_f32_e32 v180, v67, v180
	v_fma_f32 v180, v180, v181, v189
	v_cvt_pk_bf16_f32 v180, v180, v1
	ds_write_b16 v129, v180 offset:27408
	v_lshlrev_b32_e32 v180, 16, v23
	v_sub_f32_e32 v180, v180, v66
	v_mul_f32_e32 v180, v67, v180
	v_fma_f32 v180, v180, v182, v190
	v_cvt_pk_bf16_f32 v180, v180, v1
	ds_write_b16 v129, v180 offset:27680
	v_and_b32_e32 v180, 0xffff0000, v23
	v_sub_f32_e32 v180, v180, v66
	v_mul_f32_e32 v180, v67, v180
	v_fmac_f32_e32 v191, v180, v183
	v_cvt_pk_bf16_f32 v180, v191, v1
	ds_write_b16 v129, v180 offset:27952
	v_lshlrev_b32_e32 v180, 16, v24
	v_sub_f32_e32 v180, v180, v66
	v_mul_f32_e32 v180, v67, v180
	v_fma_f32 v176, v180, v176, v184
	v_cvt_pk_bf16_f32 v176, v176, v1
	ds_write_b16 v129, v176 offset:28224
	v_and_b32_e32 v176, 0xffff0000, v24
	v_sub_f32_e32 v176, v176, v66
	v_mul_f32_e32 v176, v67, v176
	v_fma_f32 v176, v176, v177, v185
	v_cvt_pk_bf16_f32 v176, v176, v1
	ds_write_b16 v129, v176 offset:28496
	v_lshlrev_b32_e32 v176, 16, v25
	v_sub_f32_e32 v176, v176, v66
	v_mul_f32_e32 v176, v67, v176
	v_fma_f32 v176, v176, v178, v186
	v_cvt_pk_bf16_f32 v176, v176, v1
	ds_write_b16 v129, v176 offset:28768
	v_and_b32_e32 v176, 0xffff0000, v25
	v_sub_f32_e32 v176, v176, v66
	v_mul_f32_e32 v176, v67, v176
	v_fmac_f32_e32 v187, v176, v179
	v_cvt_pk_bf16_f32 v176, v187, v1
	ds_write_b16 v129, v176 offset:29040
	v_cndmask_b32_e64 v176, v26, 0, s[68:69]
	v_cndmask_b32_e64 v177, 0, v27, s[4:5]
	v_cvt_pk_bf16_f32 v176, v176, v177
	v_cndmask_b32_e64 v177, v28, 0, s[6:7]
	v_cndmask_b32_e64 v178, v29, 0, s[8:9]
	v_cvt_pk_bf16_f32 v177, v177, v178
	v_add_u32_e32 v178, v125, v127
	ds_write_b64 v178, v[176:177] offset:35840
	v_cndmask_b32_e64 v176, v30, 0, s[10:11]
	v_cndmask_b32_e64 v177, 0, v31, s[12:13]
	v_cvt_pk_bf16_f32 v176, v176, v177
	v_cndmask_b32_e64 v177, v32, 0, s[14:15]
	v_cndmask_b32_e64 v179, v33, 0, s[16:17]
	v_cvt_pk_bf16_f32 v177, v177, v179
	ds_write_b64 v178, v[176:177] offset:40192
	v_cndmask_b32_e64 v176, v34, 0, s[18:19]
	v_cndmask_b32_e64 v177, 0, v35, s[20:21]
	v_cvt_pk_bf16_f32 v176, v176, v177
	v_cndmask_b32_e64 v177, v36, 0, s[22:23]
	v_cndmask_b32_e64 v179, v37, 0, s[24:25]
	v_cvt_pk_bf16_f32 v177, v177, v179
	ds_write_b64 v178, v[176:177] offset:44544
	v_cndmask_b32_e64 v176, v38, 0, s[26:27]
	v_cndmask_b32_e64 v177, 0, v39, s[28:29]
	v_cvt_pk_bf16_f32 v176, v176, v177
	v_cndmask_b32_e64 v177, v40, 0, s[30:31]
	v_cndmask_b32_e64 v179, v41, 0, s[34:35]
	v_cvt_pk_bf16_f32 v177, v177, v179
	ds_write_b64 v178, v[176:177] offset:48896
	v_cndmask_b32_e64 v176, v42, 0, s[36:37]
	v_cndmask_b32_e64 v177, 0, v43, s[38:39]
	v_cvt_pk_bf16_f32 v176, v176, v177
	v_cndmask_b32_e64 v177, v44, 0, s[40:41]
	v_cndmask_b32_e64 v179, v45, 0, s[42:43]
	v_cvt_pk_bf16_f32 v177, v177, v179
	ds_write_b64 v178, v[176:177] offset:53248
	v_cndmask_b32_e64 v176, v46, 0, s[44:45]
	v_cndmask_b32_e64 v177, 0, v47, s[46:47]
	v_cvt_pk_bf16_f32 v176, v176, v177
	v_cndmask_b32_e64 v177, v48, 0, s[48:49]
	v_cndmask_b32_e64 v179, v49, 0, s[50:51]
	v_cvt_pk_bf16_f32 v177, v177, v179
	ds_write_b64 v178, v[176:177] offset:57600
	v_cndmask_b32_e64 v176, v50, 0, s[52:53]
	v_cndmask_b32_e64 v177, 0, v51, s[54:55]
	v_cvt_pk_bf16_f32 v176, v176, v177
	v_cndmask_b32_e64 v177, v52, 0, s[56:57]
	v_cndmask_b32_e64 v179, v53, 0, s[58:59]
	v_cvt_pk_bf16_f32 v177, v177, v179
	ds_write_b64 v178, v[176:177] offset:61952
	v_cndmask_b32_e64 v176, v54, 0, s[60:61]
	v_cndmask_b32_e64 v177, 0, v55, s[62:63]
	v_cvt_pk_bf16_f32 v176, v176, v177
	v_cndmask_b32_e64 v177, v56, 0, s[64:65]
	v_cndmask_b32_e64 v178, v57, 0, s[66:67]
	v_cvt_pk_bf16_f32 v177, v177, v178
	ds_write_b64 v130, v[176:177] offset:61952
	s_waitcnt lgkmcnt(0)
	s_barrier
	s_cbranch_vccnz .LBB0_482
	v_readlane_b32 s2, v250, 54
	s_add_i32 s2, s2, s33
	s_and_b32 s2, s2, 0xffffff80
	v_add_u32_e32 v2, s2, v120
	v_or_b32_e32 v10, s2, v121
	v_readlane_b32 s2, v250, 57
	s_add_i32 s2, s2, s73
	s_and_b32 s2, s2, 0x380
	v_ashrrev_i32_e32 v11, 31, v10
	v_readlane_b32 vcc_lo, v251, 62
	v_lshl_add_u64 v[26:27], s[2:3], 0, v[96:97]
	v_lshlrev_b64 v[10:11], 11, v[10:11]
	v_readlane_b32 vcc_hi, v251, 63
	v_lshlrev_b64 v[26:27], 9, v[26:27]
	v_lshl_add_u64 v[50:51], v[98:99], 0, v[26:27]
	v_lshl_add_u64 v[10:11], vcc, 0, v[10:11]
	s_lshl_b32 vcc_lo, s2, 1
	s_mov_b32 vcc_hi, s3
	s_movk_i32 s2, 0x2000
	v_lshl_add_u64 v[10:11], v[10:11], 0, vcc
	v_add_co_u32_e32 v30, vcc, s2, v50
	s_movk_i32 s2, 0x4000
	s_nop 0
	v_addc_co_u32_e32 v31, vcc, 0, v51, vcc
	v_add_co_u32_e32 v34, vcc, s2, v50
	s_movk_i32 s2, 0x6000
	s_nop 0
	v_addc_co_u32_e32 v35, vcc, 0, v51, vcc
	v_add_co_u32_e32 v38, vcc, s2, v50
	v_ashrrev_i32_e32 v3, 31, v2
	s_nop 0
	v_addc_co_u32_e32 v39, vcc, 0, v51, vcc
	v_add_co_u32_e32 v42, vcc, 0x8000, v50
	v_lshlrev_b64 v[2:3], 7, v[2:3]
	s_nop 0
	v_addc_co_u32_e32 v43, vcc, 0, v51, vcc
	v_add_co_u32_e32 v46, vcc, 0xa000, v50
	v_lshl_add_u64 v[6:7], v[100:101], 0, v[2:3]
	s_nop 0
	v_addc_co_u32_e32 v47, vcc, 0, v51, vcc
	v_add_co_u32_e32 v52, vcc, 0xc000, v50
	v_lshl_add_u64 v[22:23], v[94:95], 1, v[10:11]
	s_nop 0
	v_addc_co_u32_e32 v53, vcc, 0, v51, vcc
	flat_load_dwordx4 v[2:5], v[6:7]
	s_nop 0
	flat_load_dwordx4 v[6:9], v[6:7] offset:16
	s_nop 0
	flat_load_dwordx4 v[10:13], v[22:23]
	flat_load_dwordx4 v[14:17], v[22:23] offset:64
	flat_load_dwordx4 v[18:21], v[22:23] offset:128
	s_nop 0
	flat_load_dwordx4 v[22:25], v[22:23] offset:192
	v_add_co_u32_e32 v54, vcc, 0xe000, v50
	global_load_dwordx4 v[26:29], v[50:51], off
	s_nop 0
	global_load_dwordx4 v[30:33], v[30:31], off
	v_addc_co_u32_e32 v55, vcc, 0, v51, vcc
	global_load_dwordx4 v[34:37], v[34:35], off
	s_nop 0
	global_load_dwordx4 v[38:41], v[38:39], off
	s_nop 0
	global_load_dwordx4 v[42:45], v[42:43], off
	s_nop 0
	global_load_dwordx4 v[46:49], v[46:47], off
	s_nop 0
	global_load_dwordx4 v[50:53], v[52:53], off
	s_nop 0
	global_load_dwordx4 v[54:57], v[54:55], off
